# EpiRes0 epilogue: hoist all residual loads to top (7 exposed latencies -> 1)
# speedup vs baseline: 1.0050x; 1.0050x over previous
; __device__ __forceinline__ float sigmoidf_(float x) { return __builtin_amdgcn_rcpf(1.0f + __expf(-x)); }
;     __device__ __forceinline__ void operator()(const f32x4 (&acc)[2][2][4][2], const Unit& u, int wr, int wc, int fr, int fq) const {
;         const int row0 = u.pm * BM + wr * 64 + fr, col0 = u.pn * BM + wc * 32 + 8 * fq; const int lane = fq * 16 + fr;
;         float rinv[8];
; #pragma unroll
;         for (int g = 0; g < 8; ++g) rinv[g] = (MODE == 1) ? tab_in[wr * 64 + fr + (g >> 2) * HALF + (g & 3) * 16] : 1.f;
;         u32x4 bc[2], pc[2];
; #pragma unroll
;         for (int bj = 0; bj < 2; ++bj) { const size_t o2 = (size_t)row0 * ldc + col0 + bj * HALF; bc[bj] = *(const u32x4*)(base + o2); if (MODE == 1) pc[bj] = *(const u32x4*)(pp + o2); }
; #pragma unroll
;         for (int g = 0; g < 8; ++g) { const int ai = g >> 2, m = g & 3; const int row = row0 + ai * HALF + m * 16; const size_t off = (size_t)row * ldc + col0;
;             f32x4 av[2][2];
; #pragma unroll
;             for (int bj = 0; bj < 2; ++bj) { f32x4 a0 = acc[ai][bj][m][0], a1 = acc[ai][bj][m][1];
;                 const f32x4 b0 = (f32x4){bflo(bc[bj].x), bfhi(bc[bj].x), bflo(bc[bj].y), bfhi(bc[bj].y)}, b1 = (f32x4){bflo(bc[bj].z), bfhi(bc[bj].z), bflo(bc[bj].w), bfhi(bc[bj].w)};
;                 if (MODE == 0) { a0 = a0 + b0; a1 = a1 + b1; }
;                 if (MODE == 1) { const f32x4 p0 = (f32x4){bflo(pc[bj].x), bfhi(pc[bj].x), bflo(pc[bj].y), bfhi(pc[bj].y)}, p1 = (f32x4){bflo(pc[bj].z), bfhi(pc[bj].z), bflo(pc[bj].w), bfhi(pc[bj].w)};
; #pragma unroll
;                     for (int j = 0; j < 4; ++j) { a0[j] = b0[j] + sigmoidf_(a0[j] * rinv[g]) * p0[j]; a1[j] = b1[j] + sigmoidf_(a1[j] * rinv[g]) * p1[j]; } }
;                 av[bj][0] = a0; av[bj][1] = a1; }
;             asm volatile("" : "+v"(av[0][0]), "+v"(av[0][1]), "+v"(av[1][0]), "+v"(av[1][1]));
;             if (g < 7) { const int rown = row0 + ((g + 1) >> 2) * HALF + ((g + 1) & 3) * 16;
; #pragma unroll
;                 for (int bj = 0; bj < 2; ++bj) { const size_t o2 = (size_t)rown * ldc + col0 + bj * HALF; bc[bj] = *(const u32x4*)(base + o2); if (MODE == 1) pc[bj] = *(const u32x4*)(pp + o2); } }
;             asm volatile("" ::: "memory");
;             float ss = 0.f;
; #pragma unroll
;             for (int bj = 0; bj < 2; ++bj) { const f32x4 a0 = av[bj][0], a1 = av[bj][1];
.LBB0_4098:
	v_mov_b32_e32 v130, v195
	s_lshl_b32 s7, s18, 8
	s_add_i32 s7, s7, s37
	v_and_b32_e32 v170, 15, v130
	v_or_b32_e32 v168, s7, v170
	s_lshl_b32 s7, s16, 8
	v_bfe_u32 v171, v130, 4, 2
	s_or_b32 s7, s7, s38
	v_lshl_or_b32 v166, v171, 3, s7
	v_ashrrev_i32_e32 v169, 31, v168
	v_readlane_b32 s18, v250, 12
	v_ashrrev_i32_e32 v167, 31, v166
	v_lshlrev_b64 v[130:131], 12, v[168:169]
	v_readlane_b32 s19, v250, 13
	v_lshlrev_b64 v[172:173], 1, v[166:167]
	v_lshlrev_b32_e32 v177, 6, v171
	v_lshl_add_u64 v[130:131], s[18:19], 0, v[130:131]
	v_lshl_add_u64 v[174:175], v[130:131], 0, v[172:173]
	global_load_dwordx4 v[130:133], v[174:175], off
	global_load_dwordx4 v[134:137], v[174:175], off offset:256
	v_lshlrev_b32_e32 v244, 12, v168
	v_lshl_add_u32 v244, v166, 1, v244
	v_add_u32_e32 v244, 0x10000, v244
	global_load_dwordx4 v[182:185], v244, s[18:19]
	global_load_dwordx4 v[186:189], v244, s[18:19] offset:256
	v_add_u32_e32 v244, 0x10000, v244
	global_load_dwordx4 v[190:193], v244, s[18:19]
	global_load_dwordx4 v[208:211], v244, s[18:19] offset:256
	v_add_u32_e32 v244, 0x10000, v244
	global_load_dwordx4 v[212:215], v244, s[18:19]
	global_load_dwordx4 v[216:219], v244, s[18:19] offset:256
	v_add_u32_e32 v244, 0x50000, v244
	global_load_dwordx4 v[220:223], v244, s[18:19]
	global_load_dwordx4 v[224:227], v244, s[18:19] offset:256
	v_add_u32_e32 v244, 0x10000, v244
	global_load_dwordx4 v[228:231], v244, s[18:19]
	global_load_dwordx4 v[232:235], v244, s[18:19] offset:256
	v_add_u32_e32 v244, 0x10000, v244
	global_load_dwordx4 v[236:239], v244, s[18:19]
	global_load_dwordx4 v[240:243], v244, s[18:19] offset:256
	v_lshlrev_b32_e32 v170, 2, v170
	s_movk_i32 s7, 0x80
	v_bitop3_b32 v178, v177, 64, v170 bitop3:0x36
	v_bitop3_b32 v177, v177, s7, v170 bitop3:0x36
	v_cmp_eq_u32_e32 vcc, 0, v171
	s_lshl_b32 s16, s16, 2
	s_ashr_i32 s17, s16, 31
	s_waitcnt vmcnt(12)
	v_lshlrev_b32_e32 v170, 16, v130
	v_and_b32_e32 v171, 0xffff0000, v130
	v_lshlrev_b32_e32 v130, 16, v131
	v_and_b32_e32 v131, 0xffff0000, v131
	v_pk_add_f32 v[126:127], v[126:127], v[170:171]
	v_or_b32_e32 v170, 16, v168
	v_pk_add_f32 v[128:129], v[128:129], v[130:131]
	v_lshlrev_b32_e32 v130, 16, v134
	v_and_b32_e32 v131, 0xffff0000, v134
	v_ashrrev_i32_e32 v171, 31, v170
	v_lshlrev_b32_e32 v180, 16, v132
	v_and_b32_e32 v181, 0xffff0000, v132
	v_lshlrev_b32_e32 v132, 16, v133
	v_and_b32_e32 v133, 0xffff0000, v133
	v_pk_add_f32 v[118:119], v[118:119], v[130:131]
	v_lshlrev_b64 v[130:131], 12, v[170:171]
	v_pk_add_f32 v[124:125], v[124:125], v[132:133]
	v_lshlrev_b32_e32 v132, 16, v135
	v_and_b32_e32 v133, 0xffff0000, v135
	v_lshlrev_b32_e32 v134, 16, v136
	v_and_b32_e32 v135, 0xffff0000, v136
	v_lshlrev_b32_e32 v136, 16, v137
	v_and_b32_e32 v137, 0xffff0000, v137
	v_lshl_add_u64 v[130:131], s[18:19], 0, v[130:131]
	v_pk_add_f32 v[122:123], v[122:123], v[180:181]
	v_pk_add_f32 v[120:121], v[120:121], v[132:133]
	v_pk_add_f32 v[116:117], v[116:117], v[136:137]
	v_pk_add_f32 v[114:115], v[114:115], v[134:135]
	v_lshl_add_u64 v[172:173], v[130:131], 0, v[172:173]
	v_add_u32_e32 v244, 0x10000, v244
	global_load_dwordx4 v[134:137], v244, s[18:19]
	global_load_dwordx4 v[130:133], v244, s[18:19] offset:256
	v_mul_f32_e32 v179, v127, v127
	v_mul_f32_e32 v180, v129, v129
	v_fmac_f32_e32 v179, v126, v126
	v_fmac_f32_e32 v180, v128, v128
	v_add_f32_e32 v179, v179, v180
	v_mul_f32_e32 v180, v123, v123
	v_fmac_f32_e32 v180, v122, v122
	v_cvt_pk_bf16_f32 v126, v126, v127
	v_cvt_pk_bf16_f32 v127, v128, v129
	v_cvt_pk_bf16_f32 v128, v122, v123
	v_mul_f32_e32 v122, v119, v119
	v_mul_f32_e32 v123, v121, v121
	v_mul_f32_e32 v181, v125, v125
	v_fmac_f32_e32 v122, v118, v118
	v_fmac_f32_e32 v123, v120, v120
	v_fmac_f32_e32 v181, v124, v124
	v_cvt_pk_bf16_f32 v129, v124, v125
	v_add_f32_e32 v122, v122, v123
	v_mul_f32_e32 v123, v115, v115
	v_mul_f32_e32 v124, v117, v117
	v_fmac_f32_e32 v123, v114, v114
	v_fmac_f32_e32 v124, v116, v116
	v_add_f32_e32 v180, v180, v181
	v_add_f32_e32 v123, v123, v124
	v_add_f32_e32 v179, v179, v180
	v_add_f32_e32 v122, v122, v123
	v_add_f32_e32 v122, v179, v122
	global_store_dwordx4 v[174:175], v[126:129], off
	v_cvt_pk_bf16_f32 v118, v118, v119
	v_cvt_pk_bf16_f32 v119, v120, v121
	v_cvt_pk_bf16_f32 v120, v114, v115
	ds_bpermute_b32 v114, v178, v122
	v_cvt_pk_bf16_f32 v121, v116, v117
	global_store_dwordx4 v[174:175], v[118:121], off offset:256
	s_waitcnt lgkmcnt(0)
	v_add_f32_e32 v114, v122, v114
	ds_bpermute_b32 v115, v177, v114
	s_and_saveexec_b64 s[18:19], vcc
	s_cbranch_execz .LBB0_4100
	v_lshlrev_b64 v[116:117], 7, v[168:169]
	v_lshl_add_u64 v[116:117], s[2:3], 0, v[116:117]
	v_lshl_add_u64 v[116:117], s[16:17], 2, v[116:117]
	s_lshl_b32 s54, s36, 2
	v_lshl_add_u64 v[116:117], v[116:117], 0, s[54:55]
	s_waitcnt lgkmcnt(0)
	v_add_f32_e32 v114, v114, v115
	global_store_dword v[116:117], v114, off
; __device__ __forceinline__ unsigned pk2(float lo, float hi) { unsigned r; asm volatile("v_cvt_pk_bf16_f32 %0, %1, %2" : "=v"(r) : "v"(lo), "v"(hi)); return r; }
;     __device__ __forceinline__ void operator()(const f32x4 (&acc)[2][2][4][2], const Unit& u, int wr, int wc, int fr, int fq) const {
;     ...
;         for (int g = 0; g < 8; ++g) { const int ai = g >> 2, m = g & 3; const int row = row0 + ai * HALF + m * 16; const size_t off = (size_t)row * ldc + col0;
;             f32x4 av[2][2];
; #pragma unroll
;             for (int bj = 0; bj < 2; ++bj) { f32x4 a0 = acc[ai][bj][m][0], a1 = acc[ai][bj][m][1];
;                 const f32x4 b0 = (f32x4){bflo(bc[bj].x), bfhi(bc[bj].x), bflo(bc[bj].y), bfhi(bc[bj].y)}, b1 = (f32x4){bflo(bc[bj].z), bfhi(bc[bj].z), bflo(bc[bj].w), bfhi(bc[bj].w)};
;                 if (MODE == 0) { a0 = a0 + b0; a1 = a1 + b1; }
;                 if (MODE == 1) { const f32x4 p0 = (f32x4){bflo(pc[bj].x), bfhi(pc[bj].x), bflo(pc[bj].y), bfhi(pc[bj].y)}, p1 = (f32x4){bflo(pc[bj].z), bfhi(pc[bj].z), bflo(pc[bj].w), bfhi(pc[bj].w)};
; #pragma unroll
;                     for (int j = 0; j < 4; ++j) { a0[j] = b0[j] + sigmoidf_(a0[j] * rinv[g]) * p0[j]; a1[j] = b1[j] + sigmoidf_(a1[j] * rinv[g]) * p1[j]; } }
;                 av[bj][0] = a0; av[bj][1] = a1; }
;             asm volatile("" : "+v"(av[0][0]), "+v"(av[0][1]), "+v"(av[1][0]), "+v"(av[1][1]));
;             if (g < 7) { const int rown = row0 + ((g + 1) >> 2) * HALF + ((g + 1) & 3) * 16;
; #pragma unroll
;                 for (int bj = 0; bj < 2; ++bj) { const size_t o2 = (size_t)rown * ldc + col0 + bj * HALF; bc[bj] = *(const u32x4*)(base + o2); if (MODE == 1) pc[bj] = *(const u32x4*)(pp + o2); } }
;             asm volatile("" ::: "memory");
;             float ss = 0.f;
; #pragma unroll
;             for (int bj = 0; bj < 2; ++bj) { const f32x4 a0 = av[bj][0], a1 = av[bj][1];
;                 ss += ((a0[0] * a0[0] + a0[1] * a0[1]) + (a0[2] * a0[2] + a0[3] * a0[3])) + ((a1[0] * a1[0] + a1[1] * a1[1]) + (a1[2] * a1[2] + a1[3] * a1[3]));
;                 u32x4 w; w.x = pk2(a0[0], a0[1]); w.y = pk2(a0[2], a0[3]); w.z = pk2(a1[0], a1[1]); w.w = pk2(a1[2], a1[3]); *(u32x4*)(out + off + bj * HALF) = w; }
;             ss += shx(ss, lane, 16); ss += shx(ss, lane, 32); if (fq == 0) rss_out[(size_t)row * 32 + u.pn * 4 + wc] = ss;
.LBB0_4100:
	s_or_b64 exec, exec, s[18:19]
	s_waitcnt vmcnt(14)
	v_lshlrev_b32_e32 v114, 16, v182
	s_waitcnt lgkmcnt(0)
	v_and_b32_e32 v115, 0xffff0000, v182
	v_lshlrev_b32_e32 v118, 16, v184
	v_and_b32_e32 v119, 0xffff0000, v184
	v_pk_add_f32 v[110:111], v[110:111], v[114:115]
	v_pk_add_f32 v[114:115], v[106:107], v[118:119]
	s_waitcnt vmcnt(14)
	v_lshlrev_b32_e32 v106, 16, v186
	v_and_b32_e32 v107, 0xffff0000, v186
	v_pk_add_f32 v[118:119], v[102:103], v[106:107]
	v_or_b32_e32 v106, 32, v168
	v_lshlrev_b32_e32 v122, 16, v188
	v_and_b32_e32 v123, 0xffff0000, v188
	v_ashrrev_i32_e32 v107, 31, v106
	v_readlane_b32 s18, v250, 12
	v_lshlrev_b32_e32 v116, 16, v183
	v_and_b32_e32 v117, 0xffff0000, v183
	v_lshlrev_b32_e32 v120, 16, v185
	v_and_b32_e32 v121, 0xffff0000, v185
	v_pk_add_f32 v[122:123], v[98:99], v[122:123]
	v_lshlrev_b64 v[98:99], 12, v[106:107]
	v_readlane_b32 s19, v250, 13
	v_pk_add_f32 v[112:113], v[112:113], v[116:117]
	v_pk_add_f32 v[116:117], v[108:109], v[120:121]
	v_lshlrev_b32_e32 v108, 16, v187
	v_and_b32_e32 v109, 0xffff0000, v187
	v_lshlrev_b32_e32 v124, 16, v189
	v_and_b32_e32 v125, 0xffff0000, v189
	v_lshl_add_u64 v[98:99], s[18:19], 0, v[98:99]
	v_pk_add_f32 v[120:121], v[104:105], v[108:109]
	v_pk_add_f32 v[124:125], v[100:101], v[124:125]
	v_lshl_add_u64 v[108:109], v[166:167], 1, v[98:99]
	v_mul_f32_e32 v126, v111, v111
	v_mul_f32_e32 v127, v113, v113
	v_fmac_f32_e32 v126, v110, v110
	v_fmac_f32_e32 v127, v112, v112
	v_add_f32_e32 v126, v126, v127
	v_mul_f32_e32 v127, v115, v115
	v_mul_f32_e32 v128, v117, v117
	v_fmac_f32_e32 v127, v114, v114
	v_fmac_f32_e32 v128, v116, v116
	v_cvt_pk_bf16_f32 v110, v110, v111
	v_cvt_pk_bf16_f32 v111, v112, v113
	v_mul_f32_e32 v112, v119, v119
	v_mul_f32_e32 v113, v121, v121
	v_add_f32_e32 v127, v127, v128
	v_fmac_f32_e32 v112, v118, v118
	v_fmac_f32_e32 v113, v120, v120
	v_add_f32_e32 v126, v126, v127
	v_add_f32_e32 v112, v112, v113
	v_mul_f32_e32 v113, v123, v123
	v_mul_f32_e32 v127, v125, v125
	v_fmac_f32_e32 v113, v122, v122
	v_fmac_f32_e32 v127, v124, v124
	v_add_f32_e32 v113, v113, v127
	v_add_f32_e32 v112, v112, v113
	v_add_f32_e32 v126, v126, v112
	ds_bpermute_b32 v127, v178, v126
	v_cvt_pk_bf16_f32 v112, v114, v115
	v_cvt_pk_bf16_f32 v113, v116, v117
	global_store_dwordx4 v[172:173], v[110:113], off
	s_waitcnt lgkmcnt(0)
	s_nop 0
	v_add_f32_e32 v110, v126, v127
	ds_bpermute_b32 v111, v177, v110
	v_cvt_pk_bf16_f32 v112, v118, v119
	v_cvt_pk_bf16_f32 v113, v120, v121
	v_cvt_pk_bf16_f32 v114, v122, v123
	v_cvt_pk_bf16_f32 v115, v124, v125
	global_store_dwordx4 v[172:173], v[112:115], off offset:256
	s_and_saveexec_b64 s[18:19], vcc
	s_cbranch_execz .LBB0_4102
	v_lshlrev_b64 v[112:113], 7, v[170:171]
	v_lshl_add_u64 v[112:113], s[2:3], 0, v[112:113]
	v_lshl_add_u64 v[112:113], s[16:17], 2, v[112:113]
	s_lshl_b32 s54, s36, 2
	v_lshl_add_u64 v[112:113], v[112:113], 0, s[54:55]
	s_waitcnt lgkmcnt(0)
	v_add_f32_e32 v110, v110, v111
	global_store_dword v[112:113], v110, off
.LBB0_4102:
	s_or_b64 exec, exec, s[18:19]
	s_waitcnt vmcnt(14)
	v_lshlrev_b32_e32 v110, 16, v190
	s_waitcnt lgkmcnt(0)
	v_and_b32_e32 v111, 0xffff0000, v190
	v_lshlrev_b32_e32 v102, 16, v191
	v_and_b32_e32 v103, 0xffff0000, v191
	v_lshlrev_b32_e32 v112, 16, v192
	v_and_b32_e32 v113, 0xffff0000, v192
	v_lshlrev_b32_e32 v104, 16, v193
	v_and_b32_e32 v105, 0xffff0000, v193
	v_pk_add_f32 v[96:97], v[96:97], v[102:103]
	v_pk_add_f32 v[102:103], v[90:91], v[112:113]
	s_waitcnt vmcnt(14)
	v_lshlrev_b32_e32 v90, 16, v208
	v_and_b32_e32 v91, 0xffff0000, v208
	v_pk_add_f32 v[104:105], v[92:93], v[104:105]
	v_lshlrev_b32_e32 v92, 16, v209
	v_and_b32_e32 v93, 0xffff0000, v209
	v_pk_add_f32 v[98:99], v[86:87], v[90:91]
	v_or_b32_e32 v90, 48, v168
	v_pk_add_f32 v[94:95], v[94:95], v[110:111]
	v_lshlrev_b32_e32 v110, 16, v210
	v_and_b32_e32 v111, 0xffff0000, v210
	v_ashrrev_i32_e32 v91, 31, v90
	v_readlane_b32 s18, v250, 12
	v_pk_add_f32 v[110:111], v[82:83], v[110:111]
	v_lshlrev_b64 v[82:83], 12, v[90:91]
	v_readlane_b32 s19, v250, 13
	v_lshlrev_b32_e32 v112, 16, v211
	v_and_b32_e32 v113, 0xffff0000, v211
	v_lshl_add_u64 v[82:83], s[18:19], 0, v[82:83]
	v_pk_add_f32 v[100:101], v[88:89], v[92:93]
	v_pk_add_f32 v[112:113], v[84:85], v[112:113]
	v_lshl_add_u64 v[92:93], v[166:167], 1, v[82:83]
	v_mul_f32_e32 v114, v95, v95
	v_mul_f32_e32 v115, v97, v97
	v_fmac_f32_e32 v114, v94, v94
	v_fmac_f32_e32 v115, v96, v96
	v_add_f32_e32 v114, v114, v115
	v_mul_f32_e32 v115, v103, v103
	v_mul_f32_e32 v116, v105, v105
	v_fmac_f32_e32 v115, v102, v102
	v_fmac_f32_e32 v116, v104, v104
	v_cvt_pk_bf16_f32 v94, v94, v95
	v_cvt_pk_bf16_f32 v95, v96, v97
	v_mul_f32_e32 v96, v99, v99
	v_mul_f32_e32 v97, v101, v101
	v_add_f32_e32 v115, v115, v116
	v_fmac_f32_e32 v96, v98, v98
	v_fmac_f32_e32 v97, v100, v100
	v_add_f32_e32 v114, v114, v115
	v_add_f32_e32 v96, v96, v97
	v_mul_f32_e32 v97, v111, v111
	v_mul_f32_e32 v115, v113, v113
	v_fmac_f32_e32 v97, v110, v110
	v_fmac_f32_e32 v115, v112, v112
	v_add_f32_e32 v97, v97, v115
	v_add_f32_e32 v96, v96, v97
	v_add_f32_e32 v114, v114, v96
	ds_bpermute_b32 v115, v178, v114
	v_cvt_pk_bf16_f32 v96, v102, v103
	v_cvt_pk_bf16_f32 v97, v104, v105
	global_store_dwordx4 v[108:109], v[94:97], off
	s_waitcnt lgkmcnt(0)
	s_nop 0
	v_add_f32_e32 v94, v114, v115
	ds_bpermute_b32 v95, v177, v94
	v_cvt_pk_bf16_f32 v96, v98, v99
	v_cvt_pk_bf16_f32 v97, v100, v101
	v_cvt_pk_bf16_f32 v98, v110, v111
	v_cvt_pk_bf16_f32 v99, v112, v113
	global_store_dwordx4 v[108:109], v[96:99], off offset:256
	s_and_saveexec_b64 s[18:19], vcc
	s_cbranch_execz .LBB0_4104
	v_lshlrev_b64 v[96:97], 7, v[106:107]
	v_lshl_add_u64 v[96:97], s[2:3], 0, v[96:97]
	v_lshl_add_u64 v[96:97], s[16:17], 2, v[96:97]
	s_lshl_b32 s54, s36, 2
	v_lshl_add_u64 v[96:97], v[96:97], 0, s[54:55]
	s_waitcnt lgkmcnt(0)
	v_add_f32_e32 v94, v94, v95
	global_store_dword v[96:97], v94, off
; __device__ __forceinline__ unsigned pk2(float lo, float hi) { unsigned r; asm volatile("v_cvt_pk_bf16_f32 %0, %1, %2" : "=v"(r) : "v"(lo), "v"(hi)); return r; }
;     __device__ __forceinline__ void operator()(const f32x4 (&acc)[2][2][4][2], const Unit& u, int wr, int wc, int fr, int fq) const {
;     ...
;         for (int g = 0; g < 8; ++g) { const int ai = g >> 2, m = g & 3; const int row = row0 + ai * HALF + m * 16; const size_t off = (size_t)row * ldc + col0;
;             f32x4 av[2][2];
; #pragma unroll
;             for (int bj = 0; bj < 2; ++bj) { f32x4 a0 = acc[ai][bj][m][0], a1 = acc[ai][bj][m][1];
;                 const f32x4 b0 = (f32x4){bflo(bc[bj].x), bfhi(bc[bj].x), bflo(bc[bj].y), bfhi(bc[bj].y)}, b1 = (f32x4){bflo(bc[bj].z), bfhi(bc[bj].z), bflo(bc[bj].w), bfhi(bc[bj].w)};
;                 if (MODE == 0) { a0 = a0 + b0; a1 = a1 + b1; }
;                 if (MODE == 1) { const f32x4 p0 = (f32x4){bflo(pc[bj].x), bfhi(pc[bj].x), bflo(pc[bj].y), bfhi(pc[bj].y)}, p1 = (f32x4){bflo(pc[bj].z), bfhi(pc[bj].z), bflo(pc[bj].w), bfhi(pc[bj].w)};
; #pragma unroll
;                     for (int j = 0; j < 4; ++j) { a0[j] = b0[j] + sigmoidf_(a0[j] * rinv[g]) * p0[j]; a1[j] = b1[j] + sigmoidf_(a1[j] * rinv[g]) * p1[j]; } }
;                 av[bj][0] = a0; av[bj][1] = a1; }
;             asm volatile("" : "+v"(av[0][0]), "+v"(av[0][1]), "+v"(av[1][0]), "+v"(av[1][1]));
;             if (g < 7) { const int rown = row0 + ((g + 1) >> 2) * HALF + ((g + 1) & 3) * 16;
; #pragma unroll
;                 for (int bj = 0; bj < 2; ++bj) { const size_t o2 = (size_t)rown * ldc + col0 + bj * HALF; bc[bj] = *(const u32x4*)(base + o2); if (MODE == 1) pc[bj] = *(const u32x4*)(pp + o2); } }
;             asm volatile("" ::: "memory");
;             float ss = 0.f;
; #pragma unroll
;             for (int bj = 0; bj < 2; ++bj) { const f32x4 a0 = av[bj][0], a1 = av[bj][1];
;                 ss += ((a0[0] * a0[0] + a0[1] * a0[1]) + (a0[2] * a0[2] + a0[3] * a0[3])) + ((a1[0] * a1[0] + a1[1] * a1[1]) + (a1[2] * a1[2] + a1[3] * a1[3]));
;                 u32x4 w; w.x = pk2(a0[0], a0[1]); w.y = pk2(a0[2], a0[3]); w.z = pk2(a1[0], a1[1]); w.w = pk2(a1[2], a1[3]); *(u32x4*)(out + off + bj * HALF) = w; }
;             ss += shx(ss, lane, 16); ss += shx(ss, lane, 32); if (fq == 0) rss_out[(size_t)row * 32 + u.pn * 4 + wc] = ss;
.LBB0_4104:
	s_or_b64 exec, exec, s[18:19]
	s_waitcnt vmcnt(14)
	v_lshlrev_b32_e32 v94, 16, v212
	s_waitcnt lgkmcnt(0)
	v_and_b32_e32 v95, 0xffff0000, v212
	v_lshlrev_b32_e32 v86, 16, v213
	v_and_b32_e32 v87, 0xffff0000, v213
	v_lshlrev_b32_e32 v96, 16, v214
	v_and_b32_e32 v97, 0xffff0000, v214
	v_lshlrev_b32_e32 v88, 16, v215
	v_and_b32_e32 v89, 0xffff0000, v215
	v_pk_add_f32 v[80:81], v[80:81], v[86:87]
	v_pk_add_f32 v[86:87], v[74:75], v[96:97]
	s_waitcnt vmcnt(14)
	v_lshlrev_b32_e32 v74, 16, v216
	v_and_b32_e32 v75, 0xffff0000, v216
	v_pk_add_f32 v[88:89], v[76:77], v[88:89]
	v_lshlrev_b32_e32 v76, 16, v217
	v_and_b32_e32 v77, 0xffff0000, v217
	v_pk_add_f32 v[82:83], v[70:71], v[74:75]
	v_add_u32_e32 v74, 0x80, v168
	v_pk_add_f32 v[78:79], v[78:79], v[94:95]
	v_lshlrev_b32_e32 v94, 16, v218
	v_and_b32_e32 v95, 0xffff0000, v218
	v_ashrrev_i32_e32 v75, 31, v74
	v_readlane_b32 s18, v250, 12
	v_pk_add_f32 v[94:95], v[66:67], v[94:95]
	v_lshlrev_b64 v[66:67], 12, v[74:75]
	v_readlane_b32 s19, v250, 13
	v_lshlrev_b32_e32 v96, 16, v219
	v_and_b32_e32 v97, 0xffff0000, v219
	v_lshl_add_u64 v[66:67], s[18:19], 0, v[66:67]
	v_pk_add_f32 v[84:85], v[72:73], v[76:77]
	v_pk_add_f32 v[96:97], v[68:69], v[96:97]
	v_lshl_add_u64 v[76:77], v[166:167], 1, v[66:67]
	v_mul_f32_e32 v98, v79, v79
	v_mul_f32_e32 v99, v81, v81
	v_fmac_f32_e32 v98, v78, v78
	v_fmac_f32_e32 v99, v80, v80
	v_add_f32_e32 v98, v98, v99
	v_mul_f32_e32 v99, v87, v87
	v_mul_f32_e32 v100, v89, v89
	v_fmac_f32_e32 v99, v86, v86
	v_fmac_f32_e32 v100, v88, v88
	v_cvt_pk_bf16_f32 v78, v78, v79
	v_cvt_pk_bf16_f32 v79, v80, v81
	v_mul_f32_e32 v80, v83, v83
	v_mul_f32_e32 v81, v85, v85
	v_add_f32_e32 v99, v99, v100
	v_fmac_f32_e32 v80, v82, v82
	v_fmac_f32_e32 v81, v84, v84
	v_add_f32_e32 v98, v98, v99
	v_add_f32_e32 v80, v80, v81
	v_mul_f32_e32 v81, v95, v95
	v_mul_f32_e32 v99, v97, v97
	v_fmac_f32_e32 v81, v94, v94
	v_fmac_f32_e32 v99, v96, v96
	v_add_f32_e32 v81, v81, v99
	v_add_f32_e32 v80, v80, v81
	v_add_f32_e32 v98, v98, v80
	ds_bpermute_b32 v99, v178, v98
	v_cvt_pk_bf16_f32 v80, v86, v87
	v_cvt_pk_bf16_f32 v81, v88, v89
	global_store_dwordx4 v[92:93], v[78:81], off
	s_waitcnt lgkmcnt(0)
	s_nop 0
	v_add_f32_e32 v78, v98, v99
	ds_bpermute_b32 v79, v177, v78
	v_cvt_pk_bf16_f32 v80, v82, v83
	v_cvt_pk_bf16_f32 v81, v84, v85
	v_cvt_pk_bf16_f32 v82, v94, v95
	v_cvt_pk_bf16_f32 v83, v96, v97
	global_store_dwordx4 v[92:93], v[80:83], off offset:256
	s_and_saveexec_b64 s[18:19], vcc
	s_cbranch_execz .LBB0_4106
	v_lshlrev_b64 v[80:81], 7, v[90:91]
	v_lshl_add_u64 v[80:81], s[2:3], 0, v[80:81]
	v_lshl_add_u64 v[80:81], s[16:17], 2, v[80:81]
	s_lshl_b32 s54, s36, 2
	v_lshl_add_u64 v[80:81], v[80:81], 0, s[54:55]
	s_waitcnt lgkmcnt(0)
	v_add_f32_e32 v78, v78, v79
	global_store_dword v[80:81], v78, off
.LBB0_4106:
	s_or_b64 exec, exec, s[18:19]
	s_waitcnt vmcnt(14)
	v_lshlrev_b32_e32 v78, 16, v220
	s_waitcnt lgkmcnt(0)
	v_and_b32_e32 v79, 0xffff0000, v220
	v_lshlrev_b32_e32 v70, 16, v221
	v_and_b32_e32 v71, 0xffff0000, v221
	v_lshlrev_b32_e32 v80, 16, v222
	v_and_b32_e32 v81, 0xffff0000, v222
	v_lshlrev_b32_e32 v72, 16, v223
	v_and_b32_e32 v73, 0xffff0000, v223
	v_pk_add_f32 v[64:65], v[64:65], v[70:71]
	v_pk_add_f32 v[70:71], v[58:59], v[80:81]
	s_waitcnt vmcnt(14)
	v_lshlrev_b32_e32 v58, 16, v224
	v_and_b32_e32 v59, 0xffff0000, v224
	v_pk_add_f32 v[72:73], v[60:61], v[72:73]
	v_lshlrev_b32_e32 v60, 16, v225
	v_and_b32_e32 v61, 0xffff0000, v225
	v_pk_add_f32 v[66:67], v[54:55], v[58:59]
	v_or_b32_e32 v58, 16, v74
	v_pk_add_f32 v[62:63], v[62:63], v[78:79]
	v_lshlrev_b32_e32 v78, 16, v226
	v_and_b32_e32 v79, 0xffff0000, v226
	v_ashrrev_i32_e32 v59, 31, v58
	v_readlane_b32 s18, v250, 12
	v_pk_add_f32 v[78:79], v[50:51], v[78:79]
	v_lshlrev_b64 v[50:51], 12, v[58:59]
	v_readlane_b32 s19, v250, 13
	v_lshlrev_b32_e32 v80, 16, v227
	v_and_b32_e32 v81, 0xffff0000, v227
	v_lshl_add_u64 v[50:51], s[18:19], 0, v[50:51]
	v_pk_add_f32 v[68:69], v[56:57], v[60:61]
	v_pk_add_f32 v[80:81], v[52:53], v[80:81]
	v_lshl_add_u64 v[60:61], v[166:167], 1, v[50:51]
	v_mul_f32_e32 v82, v63, v63
	v_mul_f32_e32 v83, v65, v65
	v_fmac_f32_e32 v82, v62, v62
	v_fmac_f32_e32 v83, v64, v64
	v_add_f32_e32 v82, v82, v83
	v_mul_f32_e32 v83, v71, v71
	v_mul_f32_e32 v84, v73, v73
	v_fmac_f32_e32 v83, v70, v70
	v_fmac_f32_e32 v84, v72, v72
	v_cvt_pk_bf16_f32 v62, v62, v63
	v_cvt_pk_bf16_f32 v63, v64, v65
	v_mul_f32_e32 v64, v67, v67
	v_mul_f32_e32 v65, v69, v69
	v_add_f32_e32 v83, v83, v84
	v_fmac_f32_e32 v64, v66, v66
	v_fmac_f32_e32 v65, v68, v68
	v_add_f32_e32 v82, v82, v83
	v_add_f32_e32 v64, v64, v65
	v_mul_f32_e32 v65, v79, v79
	v_mul_f32_e32 v83, v81, v81
	v_fmac_f32_e32 v65, v78, v78
	v_fmac_f32_e32 v83, v80, v80
	v_add_f32_e32 v65, v65, v83
	v_add_f32_e32 v64, v64, v65
	v_add_f32_e32 v82, v82, v64
	ds_bpermute_b32 v83, v178, v82
	v_cvt_pk_bf16_f32 v64, v70, v71
	v_cvt_pk_bf16_f32 v65, v72, v73
	global_store_dwordx4 v[76:77], v[62:65], off
	s_waitcnt lgkmcnt(0)
	s_nop 0
	v_add_f32_e32 v62, v82, v83
	ds_bpermute_b32 v63, v177, v62
	v_cvt_pk_bf16_f32 v64, v66, v67
	v_cvt_pk_bf16_f32 v65, v68, v69
	v_cvt_pk_bf16_f32 v66, v78, v79
	v_cvt_pk_bf16_f32 v67, v80, v81
	global_store_dwordx4 v[76:77], v[64:67], off offset:256
	s_and_saveexec_b64 s[18:19], vcc
	s_cbranch_execz .LBB0_4108
	v_lshlrev_b64 v[64:65], 7, v[74:75]
	v_lshl_add_u64 v[64:65], s[2:3], 0, v[64:65]
	v_lshl_add_u64 v[64:65], s[16:17], 2, v[64:65]
	s_lshl_b32 s54, s36, 2
	v_lshl_add_u64 v[64:65], v[64:65], 0, s[54:55]
	s_waitcnt lgkmcnt(0)
	v_add_f32_e32 v62, v62, v63
	global_store_dword v[64:65], v62, off
; __device__ __forceinline__ unsigned pk2(float lo, float hi) { unsigned r; asm volatile("v_cvt_pk_bf16_f32 %0, %1, %2" : "=v"(r) : "v"(lo), "v"(hi)); return r; }
;     __device__ __forceinline__ void operator()(const f32x4 (&acc)[2][2][4][2], const Unit& u, int wr, int wc, int fr, int fq) const {
;     ...
;         for (int g = 0; g < 8; ++g) { const int ai = g >> 2, m = g & 3; const int row = row0 + ai * HALF + m * 16; const size_t off = (size_t)row * ldc + col0;
;             f32x4 av[2][2];
; #pragma unroll
;             for (int bj = 0; bj < 2; ++bj) { f32x4 a0 = acc[ai][bj][m][0], a1 = acc[ai][bj][m][1];
;                 const f32x4 b0 = (f32x4){bflo(bc[bj].x), bfhi(bc[bj].x), bflo(bc[bj].y), bfhi(bc[bj].y)}, b1 = (f32x4){bflo(bc[bj].z), bfhi(bc[bj].z), bflo(bc[bj].w), bfhi(bc[bj].w)};
;                 if (MODE == 0) { a0 = a0 + b0; a1 = a1 + b1; }
;                 if (MODE == 1) { const f32x4 p0 = (f32x4){bflo(pc[bj].x), bfhi(pc[bj].x), bflo(pc[bj].y), bfhi(pc[bj].y)}, p1 = (f32x4){bflo(pc[bj].z), bfhi(pc[bj].z), bflo(pc[bj].w), bfhi(pc[bj].w)};
; #pragma unroll
;                     for (int j = 0; j < 4; ++j) { a0[j] = b0[j] + sigmoidf_(a0[j] * rinv[g]) * p0[j]; a1[j] = b1[j] + sigmoidf_(a1[j] * rinv[g]) * p1[j]; } }
;                 av[bj][0] = a0; av[bj][1] = a1; }
;             asm volatile("" : "+v"(av[0][0]), "+v"(av[0][1]), "+v"(av[1][0]), "+v"(av[1][1]));
;             if (g < 7) { const int rown = row0 + ((g + 1) >> 2) * HALF + ((g + 1) & 3) * 16;
; #pragma unroll
;                 for (int bj = 0; bj < 2; ++bj) { const size_t o2 = (size_t)rown * ldc + col0 + bj * HALF; bc[bj] = *(const u32x4*)(base + o2); if (MODE == 1) pc[bj] = *(const u32x4*)(pp + o2); } }
;             asm volatile("" ::: "memory");
;             float ss = 0.f;
; #pragma unroll
;             for (int bj = 0; bj < 2; ++bj) { const f32x4 a0 = av[bj][0], a1 = av[bj][1];
;                 ss += ((a0[0] * a0[0] + a0[1] * a0[1]) + (a0[2] * a0[2] + a0[3] * a0[3])) + ((a1[0] * a1[0] + a1[1] * a1[1]) + (a1[2] * a1[2] + a1[3] * a1[3]));
;                 u32x4 w; w.x = pk2(a0[0], a0[1]); w.y = pk2(a0[2], a0[3]); w.z = pk2(a1[0], a1[1]); w.w = pk2(a1[2], a1[3]); *(u32x4*)(out + off + bj * HALF) = w; }
;             ss += shx(ss, lane, 16); ss += shx(ss, lane, 32); if (fq == 0) rss_out[(size_t)row * 32 + u.pn * 4 + wc] = ss;
.LBB0_4108:
	s_or_b64 exec, exec, s[18:19]
	s_waitcnt vmcnt(14)
	v_lshlrev_b32_e32 v62, 16, v228
	s_waitcnt lgkmcnt(0)
	v_and_b32_e32 v63, 0xffff0000, v228
	v_lshlrev_b32_e32 v54, 16, v229
	v_and_b32_e32 v55, 0xffff0000, v229
	v_lshlrev_b32_e32 v64, 16, v230
	v_and_b32_e32 v65, 0xffff0000, v230
	v_lshlrev_b32_e32 v56, 16, v231
	v_and_b32_e32 v57, 0xffff0000, v231
	v_pk_add_f32 v[48:49], v[48:49], v[54:55]
	v_pk_add_f32 v[54:55], v[42:43], v[64:65]
	s_waitcnt vmcnt(14)
	v_lshlrev_b32_e32 v42, 16, v232
	v_and_b32_e32 v43, 0xffff0000, v232
	v_pk_add_f32 v[56:57], v[44:45], v[56:57]
	v_lshlrev_b32_e32 v44, 16, v233
	v_and_b32_e32 v45, 0xffff0000, v233
	v_pk_add_f32 v[50:51], v[38:39], v[42:43]
	v_or_b32_e32 v42, 32, v74
	v_pk_add_f32 v[46:47], v[46:47], v[62:63]
	v_lshlrev_b32_e32 v62, 16, v234
	v_and_b32_e32 v63, 0xffff0000, v234
	v_ashrrev_i32_e32 v43, 31, v42
	v_readlane_b32 s18, v250, 12
	v_pk_add_f32 v[62:63], v[34:35], v[62:63]
	v_lshlrev_b64 v[34:35], 12, v[42:43]
	v_readlane_b32 s19, v250, 13
	v_lshlrev_b32_e32 v64, 16, v235
	v_and_b32_e32 v65, 0xffff0000, v235
	v_lshl_add_u64 v[34:35], s[18:19], 0, v[34:35]
	v_pk_add_f32 v[52:53], v[40:41], v[44:45]
	v_pk_add_f32 v[64:65], v[36:37], v[64:65]
	v_lshl_add_u64 v[44:45], v[166:167], 1, v[34:35]
	v_mul_f32_e32 v66, v47, v47
	v_mul_f32_e32 v67, v49, v49
	v_fmac_f32_e32 v66, v46, v46
	v_fmac_f32_e32 v67, v48, v48
	v_add_f32_e32 v66, v66, v67
	v_mul_f32_e32 v67, v55, v55
	v_mul_f32_e32 v68, v57, v57
	v_fmac_f32_e32 v67, v54, v54
	v_fmac_f32_e32 v68, v56, v56
	v_cvt_pk_bf16_f32 v46, v46, v47
	v_cvt_pk_bf16_f32 v47, v48, v49
	v_mul_f32_e32 v48, v51, v51
	v_mul_f32_e32 v49, v53, v53
	v_add_f32_e32 v67, v67, v68
	v_fmac_f32_e32 v48, v50, v50
	v_fmac_f32_e32 v49, v52, v52
	v_add_f32_e32 v66, v66, v67
	v_add_f32_e32 v48, v48, v49
	v_mul_f32_e32 v49, v63, v63
	v_mul_f32_e32 v67, v65, v65
	v_fmac_f32_e32 v49, v62, v62
	v_fmac_f32_e32 v67, v64, v64
	v_add_f32_e32 v49, v49, v67
	v_add_f32_e32 v48, v48, v49
	v_add_f32_e32 v66, v66, v48
	ds_bpermute_b32 v67, v178, v66
	v_cvt_pk_bf16_f32 v48, v54, v55
	v_cvt_pk_bf16_f32 v49, v56, v57
	global_store_dwordx4 v[60:61], v[46:49], off
	s_waitcnt lgkmcnt(0)
	s_nop 0
	v_add_f32_e32 v46, v66, v67
	ds_bpermute_b32 v47, v177, v46
	v_cvt_pk_bf16_f32 v48, v50, v51
	v_cvt_pk_bf16_f32 v49, v52, v53
	v_cvt_pk_bf16_f32 v50, v62, v63
	v_cvt_pk_bf16_f32 v51, v64, v65
	global_store_dwordx4 v[60:61], v[48:51], off offset:256
	s_and_saveexec_b64 s[18:19], vcc
	s_cbranch_execz .LBB0_4110
	v_lshlrev_b64 v[48:49], 7, v[58:59]
	v_lshl_add_u64 v[48:49], s[2:3], 0, v[48:49]
	v_lshl_add_u64 v[48:49], s[16:17], 2, v[48:49]
	s_lshl_b32 s54, s36, 2
	v_lshl_add_u64 v[48:49], v[48:49], 0, s[54:55]
	s_waitcnt lgkmcnt(0)
	v_add_f32_e32 v46, v46, v47
	global_store_dword v[48:49], v46, off
; __device__ __forceinline__ unsigned pk2(float lo, float hi) { unsigned r; asm volatile("v_cvt_pk_bf16_f32 %0, %1, %2" : "=v"(r) : "v"(lo), "v"(hi)); return r; }
;     __device__ __forceinline__ void operator()(const f32x4 (&acc)[2][2][4][2], const Unit& u, int wr, int wc, int fr, int fq) const {
;     ...
;         for (int g = 0; g < 8; ++g) { const int ai = g >> 2, m = g & 3; const int row = row0 + ai * HALF + m * 16; const size_t off = (size_t)row * ldc + col0;
;             f32x4 av[2][2];
; #pragma unroll
;             for (int bj = 0; bj < 2; ++bj) { f32x4 a0 = acc[ai][bj][m][0], a1 = acc[ai][bj][m][1];
;                 const f32x4 b0 = (f32x4){bflo(bc[bj].x), bfhi(bc[bj].x), bflo(bc[bj].y), bfhi(bc[bj].y)}, b1 = (f32x4){bflo(bc[bj].z), bfhi(bc[bj].z), bflo(bc[bj].w), bfhi(bc[bj].w)};
;                 if (MODE == 0) { a0 = a0 + b0; a1 = a1 + b1; }
;                 if (MODE == 1) { const f32x4 p0 = (f32x4){bflo(pc[bj].x), bfhi(pc[bj].x), bflo(pc[bj].y), bfhi(pc[bj].y)}, p1 = (f32x4){bflo(pc[bj].z), bfhi(pc[bj].z), bflo(pc[bj].w), bfhi(pc[bj].w)};
; #pragma unroll
;                     for (int j = 0; j < 4; ++j) { a0[j] = b0[j] + sigmoidf_(a0[j] * rinv[g]) * p0[j]; a1[j] = b1[j] + sigmoidf_(a1[j] * rinv[g]) * p1[j]; } }
;                 av[bj][0] = a0; av[bj][1] = a1; }
;             asm volatile("" : "+v"(av[0][0]), "+v"(av[0][1]), "+v"(av[1][0]), "+v"(av[1][1]));
;             if (g < 7) { const int rown = row0 + ((g + 1) >> 2) * HALF + ((g + 1) & 3) * 16;
; #pragma unroll
;                 for (int bj = 0; bj < 2; ++bj) { const size_t o2 = (size_t)rown * ldc + col0 + bj * HALF; bc[bj] = *(const u32x4*)(base + o2); if (MODE == 1) pc[bj] = *(const u32x4*)(pp + o2); } }
;             asm volatile("" ::: "memory");
;             float ss = 0.f;
; #pragma unroll
;             for (int bj = 0; bj < 2; ++bj) { const f32x4 a0 = av[bj][0], a1 = av[bj][1];
;                 ss += ((a0[0] * a0[0] + a0[1] * a0[1]) + (a0[2] * a0[2] + a0[3] * a0[3])) + ((a1[0] * a1[0] + a1[1] * a1[1]) + (a1[2] * a1[2] + a1[3] * a1[3]));
;                 u32x4 w; w.x = pk2(a0[0], a0[1]); w.y = pk2(a0[2], a0[3]); w.z = pk2(a1[0], a1[1]); w.w = pk2(a1[2], a1[3]); *(u32x4*)(out + off + bj * HALF) = w; }
;             ss += shx(ss, lane, 16); ss += shx(ss, lane, 32); if (fq == 0) rss_out[(size_t)row * 32 + u.pn * 4 + wc] = ss;
;         }
.LBB0_4110:
	s_or_b64 exec, exec, s[18:19]
	s_waitcnt vmcnt(14)
	v_lshlrev_b32_e32 v46, 16, v236
	s_waitcnt lgkmcnt(0)
	v_and_b32_e32 v47, 0xffff0000, v236
	v_lshlrev_b32_e32 v38, 16, v237
	v_and_b32_e32 v39, 0xffff0000, v237
	v_lshlrev_b32_e32 v48, 16, v238
	v_and_b32_e32 v49, 0xffff0000, v238
	v_lshlrev_b32_e32 v40, 16, v239
	v_and_b32_e32 v41, 0xffff0000, v239
	v_pk_add_f32 v[32:33], v[32:33], v[38:39]
	v_pk_add_f32 v[38:39], v[26:27], v[48:49]
	s_waitcnt vmcnt(14)
	v_lshlrev_b32_e32 v26, 16, v240
	v_and_b32_e32 v27, 0xffff0000, v240
	v_pk_add_f32 v[40:41], v[28:29], v[40:41]
	v_lshlrev_b32_e32 v28, 16, v241
	v_and_b32_e32 v29, 0xffff0000, v241
	v_pk_add_f32 v[34:35], v[22:23], v[26:27]
	v_or_b32_e32 v26, 48, v74
	v_pk_add_f32 v[30:31], v[30:31], v[46:47]
	v_lshlrev_b32_e32 v46, 16, v242
	v_and_b32_e32 v47, 0xffff0000, v242
	v_ashrrev_i32_e32 v27, 31, v26
	v_readlane_b32 s18, v250, 12
	v_pk_add_f32 v[46:47], v[18:19], v[46:47]
	v_lshlrev_b64 v[18:19], 12, v[26:27]
	v_readlane_b32 s19, v250, 13
	v_lshlrev_b32_e32 v48, 16, v243
	v_and_b32_e32 v49, 0xffff0000, v243
	v_lshl_add_u64 v[18:19], s[18:19], 0, v[18:19]
	v_pk_add_f32 v[36:37], v[24:25], v[28:29]
	v_pk_add_f32 v[48:49], v[20:21], v[48:49]
	v_lshl_add_u64 v[28:29], v[166:167], 1, v[18:19]
	v_mul_f32_e32 v50, v31, v31
	v_mul_f32_e32 v51, v33, v33
	v_fmac_f32_e32 v50, v30, v30
	v_fmac_f32_e32 v51, v32, v32
	v_add_f32_e32 v50, v50, v51
	v_mul_f32_e32 v51, v39, v39
	v_mul_f32_e32 v52, v41, v41
	v_fmac_f32_e32 v51, v38, v38
	v_fmac_f32_e32 v52, v40, v40
	v_cvt_pk_bf16_f32 v30, v30, v31
	v_cvt_pk_bf16_f32 v31, v32, v33
	v_mul_f32_e32 v32, v35, v35
	v_mul_f32_e32 v33, v37, v37
	v_add_f32_e32 v51, v51, v52
	v_fmac_f32_e32 v32, v34, v34
	v_fmac_f32_e32 v33, v36, v36
	v_add_f32_e32 v50, v50, v51
	v_add_f32_e32 v32, v32, v33
	v_mul_f32_e32 v33, v47, v47
	v_mul_f32_e32 v51, v49, v49
	v_fmac_f32_e32 v33, v46, v46
	v_fmac_f32_e32 v51, v48, v48
	v_add_f32_e32 v33, v33, v51
	v_add_f32_e32 v32, v32, v33
	v_add_f32_e32 v50, v50, v32
	ds_bpermute_b32 v51, v178, v50
	v_cvt_pk_bf16_f32 v32, v38, v39
	v_cvt_pk_bf16_f32 v33, v40, v41
	global_store_dwordx4 v[44:45], v[30:33], off
	s_waitcnt lgkmcnt(0)
	s_nop 0
	v_add_f32_e32 v30, v50, v51
	ds_bpermute_b32 v31, v177, v30
	v_cvt_pk_bf16_f32 v32, v34, v35
	v_cvt_pk_bf16_f32 v33, v36, v37
	v_cvt_pk_bf16_f32 v34, v46, v47
	v_cvt_pk_bf16_f32 v35, v48, v49
	global_store_dwordx4 v[44:45], v[32:35], off offset:256
	s_and_saveexec_b64 s[18:19], vcc
	s_cbranch_execz .LBB0_4112
	v_lshlrev_b64 v[32:33], 7, v[42:43]
	v_lshl_add_u64 v[32:33], s[2:3], 0, v[32:33]
	v_lshl_add_u64 v[32:33], s[16:17], 2, v[32:33]
	s_lshl_b32 s54, s36, 2
	v_lshl_add_u64 v[32:33], v[32:33], 0, s[54:55]
	s_waitcnt lgkmcnt(0)
	v_add_f32_e32 v30, v30, v31
	global_store_dword v[32:33], v30, off
.LBB0_4112:
	s_or_b64 exec, exec, s[18:19]
	s_waitcnt vmcnt(14)
	v_lshlrev_b32_e32 v30, 16, v134
	s_waitcnt lgkmcnt(0)
	v_and_b32_e32 v31, 0xffff0000, v134
	v_lshlrev_b32_e32 v22, 16, v135
	v_and_b32_e32 v23, 0xffff0000, v135
	v_lshlrev_b32_e32 v32, 16, v136
	v_and_b32_e32 v33, 0xffff0000, v136
	v_lshlrev_b32_e32 v24, 16, v137
	v_and_b32_e32 v25, 0xffff0000, v137
	v_pk_add_f32 v[16:17], v[16:17], v[22:23]
	v_pk_add_f32 v[12:13], v[12:13], v[24:25]
	s_waitcnt vmcnt(14)
	v_lshlrev_b32_e32 v22, 16, v130
	v_and_b32_e32 v23, 0xffff0000, v130
	v_lshlrev_b32_e32 v18, 16, v131
	v_and_b32_e32 v19, 0xffff0000, v131
	v_lshlrev_b32_e32 v24, 16, v132
	v_and_b32_e32 v25, 0xffff0000, v132
	v_lshlrev_b32_e32 v20, 16, v133
	v_and_b32_e32 v21, 0xffff0000, v133
	v_pk_add_f32 v[14:15], v[14:15], v[30:31]
	v_pk_add_f32 v[10:11], v[10:11], v[32:33]
	v_pk_add_f32 v[8:9], v[8:9], v[18:19]
	v_pk_add_f32 v[6:7], v[6:7], v[22:23]
	v_pk_add_f32 v[20:21], v[4:5], v[20:21]
	v_pk_add_f32 v[18:19], v[2:3], v[24:25]
	s_nop 0
	s_nop 0
	v_mul_f32_e32 v2, v15, v15
	v_mul_f32_e32 v3, v17, v17
	v_fmac_f32_e32 v2, v14, v14
	v_fmac_f32_e32 v3, v16, v16
	v_add_f32_e32 v2, v2, v3
	v_mul_f32_e32 v3, v11, v11
	v_mul_f32_e32 v4, v13, v13
	v_fmac_f32_e32 v3, v10, v10
	v_fmac_f32_e32 v4, v12, v12
	v_add_f32_e32 v3, v3, v4
	v_add_f32_e32 v4, v2, v3
	v_cvt_pk_bf16_f32 v2, v14, v15
	v_mul_f32_e32 v5, v7, v7
	v_mul_f32_e32 v14, v9, v9
	v_fmac_f32_e32 v5, v6, v6
	v_fmac_f32_e32 v14, v8, v8
	v_add_f32_e32 v5, v5, v14
	v_mul_f32_e32 v14, v19, v19
	v_mul_f32_e32 v15, v21, v21
	v_fmac_f32_e32 v14, v18, v18
	v_fmac_f32_e32 v15, v20, v20
	v_add_f32_e32 v14, v14, v15
	v_add_f32_e32 v5, v5, v14
	v_add_f32_e32 v14, v4, v5
	ds_bpermute_b32 v15, v178, v14
	v_cvt_pk_bf16_f32 v3, v16, v17
	v_cvt_pk_bf16_f32 v4, v10, v11
	v_cvt_pk_bf16_f32 v5, v12, v13
	global_store_dwordx4 v[28:29], v[2:5], off
	s_waitcnt lgkmcnt(0)
	s_nop 0
	v_add_f32_e32 v2, v14, v15
	ds_bpermute_b32 v3, v177, v2
	v_cvt_pk_bf16_f32 v4, v6, v7
	v_cvt_pk_bf16_f32 v5, v8, v9
	v_cvt_pk_bf16_f32 v6, v18, v19
	v_cvt_pk_bf16_f32 v7, v20, v21
	global_store_dwordx4 v[28:29], v[4:7], off offset:256
	s_and_saveexec_b64 s[18:19], vcc
	s_cbranch_execz .LBB0_4114
	v_lshlrev_b64 v[4:5], 7, v[26:27]
	v_lshl_add_u64 v[4:5], s[2:3], 0, v[4:5]
	v_lshl_add_u64 v[4:5], s[16:17], 2, v[4:5]
	s_lshl_b32 s54, s36, 2
	v_lshl_add_u64 v[4:5], v[4:5], 0, s[54:55]
	s_waitcnt lgkmcnt(0)
	v_add_f32_e32 v2, v2, v3
	global_store_dword v[4:5], v2, off
